# next_unit computed by wave 0 only and handed to waves 1-7 through LDS at the unit's second K iteration
# speedup vs baseline: 1.0107x; 1.0107x over previous
; __device__ __forceinline__ void next_unit(const Call& C, int i, int& pm, int& pn, int& kp0, int& np, int& slice) {
;     const long L = (long)i * C.G + C.c;
;     const int nM = C.j0.nM, nN = C.j0.nN, nwg = nM * nN, P = C.K / (2 * BK);
;     const int S = C.j0.S, nsl = C.j0.cM * nN * S;
;     pm = -1; pn = 0; kp0 = 0; np = P; slice = -1;
;     if (L < nwg) {
;         int wgid = (int)L; { const int q = nwg / NXCD, r = nwg % NXCD, xcd = wgid % NXCD, off = wgid / NXCD; wgid = (xcd < r ? xcd * (q + 1) : r * (q + 1) + (xcd - r) * q) + off; }
;         const int nig = WGM * nN, gid = wgid / nig, fm = gid * WGM, gsz = (nM - fm) < WGM ? (nM - fm) : WGM;
;         pm = fm + ((wgid % nig) % gsz); pn = (wgid % nig) / gsz;
;     } else if (L < (long)nwg + nsl) {
;         const int Ls = (int)(L - nwg);
;         const int tile = Ls / S, sl = Ls - tile * S, base = P / S, rem = P - base * S;
;         pm = nM + tile / nN; pn = tile % nN; slice = sl; np = base + (sl < rem ? 1 : 0); kp0 = sl * base + (sl < rem ? sl : rem);
;     }
; __device__ __forceinline__ void gemm_phase(LAS unsigned char* lds, const Call& C, const int tid, const Args& args) {
;     ...
;         next_unit(C, ui + 1, nxt.pm, nxt.pn, nxt.kp0, nxt.np, nxt.slice);
.LBB0_267:
	s_add_i32 s92, s92, 1
	s_cmp_eq_u32 s20, 0
	s_cbranch_scc1 .Lnu_compute
	s_cmp_lt_u32 s16, 2
	s_cbranch_scc1 .Lnu_compute
	s_branch .LBB0_280
.Lnu_compute:
	s_mul_i32 s5, s92, s53
	s_mul_hi_u32 s12, s92, s11
	s_add_i32 s12, s12, s5
	s_mul_i32 s5, s92, s11
	s_add_u32 s36, s5, s21
	s_addc_u32 s37, s12, s51
	v_mov_b64_e32 v[0:1], s[26:27]
	v_cmp_ge_i64_e32 vcc, s[36:37], v[0:1]
	s_mov_b64 s[38:39], -1
	s_and_b64 vcc, exec, vcc
	s_cbranch_vccz .LBB0_270
	v_readlane_b32 s12, v255, 33
	v_readlane_b32 s13, v255, 34
	s_mov_b64 s[38:39], 0
	s_nop 0
	v_mov_b64_e32 v[0:1], s[12:13]
	v_cmp_ge_i64_e32 vcc, s[36:37], v[0:1]
	s_cbranch_vccnz .LBB0_314
	s_sub_i32 s5, s36, s26
	s_abs_i32 s13, s5
	v_readlane_b32 s17, v255, 25
	s_mul_hi_u32 s17, s13, s17
	v_readlane_b32 s34, v254, 31
	s_mul_i32 s24, s17, s34
	s_sub_i32 s13, s13, s24
	s_ashr_i32 s12, s5, 31
	s_add_i32 s24, s17, 1
	s_sub_i32 s25, s13, s34
	s_cmp_ge_u32 s13, s34
	s_cselect_b32 s17, s24, s17
	s_cselect_b32 s13, s25, s13
	s_add_i32 s24, s17, 1
	s_cmp_ge_u32 s13, s34
	s_cselect_b32 s13, s24, s17
	s_xor_b32 s13, s13, s12
	s_sub_i32 s12, s13, s12
	s_mul_i32 s13, s12, s34
	s_sub_i32 s91, s5, s13
	s_ashr_i32 s5, s12, 31
	v_readlane_b32 s13, v255, 31
	s_xor_b32 s5, s5, s13
	s_abs_i32 s13, s12
	v_readlane_b32 s17, v255, 26
	s_mul_hi_u32 s17, s13, s17
	s_mul_i32 s24, s17, s97
	s_sub_i32 s13, s13, s24
	s_add_i32 s24, s17, 1
	s_sub_i32 s25, s13, s97
	s_cmp_ge_u32 s13, s97
	s_cselect_b32 s17, s24, s17
	s_cselect_b32 s13, s25, s13
	s_add_i32 s24, s17, 1
	s_cmp_ge_u32 s13, s97
	s_cselect_b32 s13, s24, s17
	s_xor_b32 s13, s13, s5
	s_sub_i32 s13, s13, s5
	v_readlane_b32 s5, v254, 40
	v_readlane_b32 s17, v254, 16
	s_add_i32 s5, s13, s5
	s_mul_i32 s13, s13, s17
	s_sub_i32 s95, s12, s13
	v_readlane_b32 s17, v255, 30
	s_cmp_lt_i32 s91, s17
	s_cselect_b64 s[12:13], -1, 0
	s_cmp_lg_u64 s[12:13], 0
	v_readlane_b32 s12, v255, 29
	s_addc_u32 s54, s12, 0
	s_mul_i32 s12, s91, s12
	s_min_i32 s13, s91, s17
	s_add_i32 s12, s13, s12
	s_ashr_i32 s13, s12, 31
	s_lshl_b64 s[40:41], s[12:13], 8

; __device__ __forceinline__ void gemm_phase(LAS unsigned char* lds, const Call& C, const int tid, const Args& args) {
;     ...
;         next_unit(C, ui + 1, nxt.pm, nxt.pn, nxt.kp0, nxt.np, nxt.slice);
;         const bool has_next = nxt.pm >= 0;
;         const char* nA = has_next ? PG8_APTR(nxt) : cA; const char* nB = has_next ? PG8_BPTR(nxt) : cB;
.LBB0_280:
	s_cmp_lg_u32 s20, 0
	s_cbranch_scc1 .Lnu_noprod
	s_and_b32 vcc_lo, s92, 1
	s_lshl_b32 vcc_lo, vcc_lo, 6
	s_add_i32 vcc_lo, vcc_lo, 0x20200
	v_mov_b32_e32 v200, s91
	v_mov_b32_e32 v201, s54
	v_mov_b32_e32 v202, s95
	v_mov_b32_e32 v203, s5
	v_mov_b32_e32 v206, s48
	v_mov_b32_e32 v207, s49
	v_mov_b32_e32 v208, s86
	v_mov_b32_e32 v209, s87
	v_mov_b32_e32 v210, s36
	v_mov_b32_e32 v211, s37
	v_mov_b32_e32 v212, vcc_lo
	s_mov_b64 exec, 1
	ds_write_b128 v212, v[200:203]
	ds_write_b128 v212, v[206:209] offset:16
	ds_write_b64 v212, v[210:211] offset:32
	s_mov_b64 exec, -1

; __device__ __forceinline__ void gemm_phase(LAS unsigned char* lds, const Call& C, const int tid, const Args& args) {
;     ...
;         next_unit(C, ui + 1, nxt.pm, nxt.pn, nxt.kp0, nxt.np, nxt.slice);
;         const bool has_next = nxt.pm >= 0;
;         const char* nA = has_next ? PG8_APTR(nxt) : cA; const char* nB = has_next ? PG8_BPTR(nxt) : cB;
;         const int nt = 2 * cur.np;
;         for (int t = 0; t < nt; t += 2) {
;             const bool last = (t == nt - 2);
;             const char* a1 = cA + (size_t)(t + 1) * kstep;
;             const char* a2 = last ? nA : cA + (size_t)(t + 2) * kstep; const char* b2 = last ? nB : cB + (size_t)(t + 2) * kstep;
.LBB0_282:
	s_cmp_lg_u32 s24, 2
	s_cbranch_scc1 .Lnu_nofetch
	s_cmp_eq_u32 s20, 0
	s_cbranch_scc1 .Lnu_nofetch
	s_and_b32 vcc_lo, s92, 1
	s_lshl_b32 vcc_lo, vcc_lo, 6
	s_add_i32 vcc_lo, vcc_lo, 0x20200
	v_mov_b32_e32 v212, vcc_lo
	ds_read_b128 v[200:203], v212
	ds_read_b128 v[206:209], v212 offset:16
	ds_read_b64 v[210:211], v212 offset:32
	s_waitcnt lgkmcnt(0)
	v_readfirstlane_b32 s91, v200
	v_readfirstlane_b32 s54, v201
	v_readfirstlane_b32 s95, v202
	v_readfirstlane_b32 s5, v203
	v_readfirstlane_b32 s48, v206
	v_readfirstlane_b32 s49, v207
	v_readfirstlane_b32 s86, v208
	v_readfirstlane_b32 s87, v209
	v_readfirstlane_b32 s36, v210
	v_readfirstlane_b32 s37, v211
	s_nop 3
